# prologue: waves 4-7 run the compute-bound parts (WOVT/WABST) first, waves 0-3 the streaming parts first, so they overlap per SIMD
# speedup vs baseline: 1.0256x; 1.0034x over previous
_Z8yoco_fwd6Params:
	s_mov_b32 s97, 0
	s_load_dwordx2 s[28:29], s[0:1], 0x140
	s_add_u32 s24, s0, 0x140
	s_addc_u32 s25, s1, 0
	v_and_b32_e32 v210, 0x3ff, v0
	v_cmp_eq_u32_e64 s[6:7], 0, v210
	s_mov_b64 s[4:5], exec
	s_nop 0
	v_writelane_b32 v255, s6, 0
	s_nop 1
	v_writelane_b32 v255, s7, 1
	s_and_b64 s[6:7], s[4:5], s[6:7]
	s_mov_b64 exec, s[6:7]
	s_cbranch_execz .LBB0_2
	s_add_i32 s3, 0, 0x257d0
	v_mov_b32_e32 v1, 0
	v_mov_b32_e32 v2, s3
	s_add_i32 s3, 0, 0x257d4
	ds_write_b32 v2, v1
	v_mov_b32_e32 v2, s3
	ds_write_b32 v2, v1

.Lp0_pre:
	v_mov_b32_e32 v1, v210
	s_lshl_b32 s85, s2, 3
	v_readfirstlane_b32 s75, v1
	s_ashr_i32 s33, s75, 6
	s_add_i32 s3, s33, s85
	v_and_b32_e32 v66, 63, v1
	s_cmp_eq_u32 s97, 2
	s_cbranch_scc1 .Lp0_A
	s_mov_b32 s97, 0
	s_bitcmp1_b32 s33, 2
	s_cbranch_scc0 .Lp0_A
	s_mov_b32 s97, 1
	s_mul_i32 s39, s33, 0x4100
	s_add_i32 s74, s39, 0
	s_lshl_b32 s38, s28, 3
	s_branch .Lp0_D
.Lp0_A:
	s_cmpk_gt_i32 s3, 0x20ff
	v_mbcnt_lo_u32_b32 v254, -1, 0
	s_cbranch_scc1 .LBB0_24
	v_mbcnt_hi_u32_b32 v4, -1, v254
	v_and_b32_e32 v5, 64, v4
	v_add_u32_e32 v5, 64, v5
	v_xor_b32_e32 v6, 1, v4
	v_cmp_lt_i32_e32 vcc, v6, v5
	s_load_dwordx4 s[12:15], s[0:1], 0x0
	s_lshl_b32 s10, s3, 1
	v_cndmask_b32_e32 v6, v4, v6, vcc
	v_lshlrev_b32_e32 v26, 2, v6
	v_xor_b32_e32 v6, 2, v4
	v_cmp_lt_i32_e32 vcc, v6, v5
	v_lshlrev_b32_e32 v2, 2, v66
	v_mov_b32_e32 v3, 0
	v_cndmask_b32_e32 v6, v4, v6, vcc
	v_lshlrev_b32_e32 v27, 2, v6
	v_xor_b32_e32 v6, 4, v4
	v_cmp_lt_i32_e32 vcc, v6, v5
	s_lshl_b32 s18, s28, 4
	s_ashr_i32 s11, s10, 31
	v_cndmask_b32_e32 v6, v4, v6, vcc
	v_lshlrev_b32_e32 v28, 2, v6
	v_xor_b32_e32 v6, 8, v4
	v_cmp_lt_i32_e32 vcc, v6, v5
	s_mov_b64 s[6:7], 0x7cac800
	s_ashr_i32 s19, s18, 31
	v_cndmask_b32_e32 v6, v4, v6, vcc
	v_lshlrev_b32_e32 v29, 2, v6
	v_xor_b32_e32 v6, 16, v4
	v_cmp_lt_i32_e32 vcc, v6, v5
	s_lshl_b64 s[20:21], s[10:11], 11
	s_lshl_b64 s[22:23], s[10:11], 6
	v_cndmask_b32_e32 v6, v4, v6, vcc
	v_lshlrev_b32_e32 v30, 2, v6
	v_xor_b32_e32 v6, 32, v4
	v_cmp_lt_i32_e32 vcc, v6, v5
	s_mov_b32 s17, 0
	v_cmp_gt_u32_e64 s[4:5], 32, v66
	v_cndmask_b32_e32 v4, v4, v6, vcc
	v_lshlrev_b32_e32 v31, 2, v4
	v_lshl_add_u64 v[4:5], s[30:31], 0, v[2:3]
	v_lshl_add_u64 v[18:19], v[4:5], 0, s[6:7]
	v_cmp_eq_u32_e64 s[6:7], 0, v66
	v_cmp_gt_u32_e64 s[8:9], 16, v66
	v_lshl_or_b32 v20, v66, 3, s20
	v_mov_b32_e32 v21, s21
	s_lshl_b64 s[20:21], s[18:19], 11
	v_lshl_add_u64 v[22:23], s[22:23], 0, v[2:3]
	s_lshl_b64 s[22:23], s[18:19], 6
	v_lshlrev_b32_e32 v32, 2, v2
	s_mov_b32 s42, 0x5894000
	s_branch .LBB0_9

.Lp0_D:
	s_cmp_eq_u32 s97, 2
	s_cbranch_scc1 .LBB0_186
	s_cmpk_gt_i32 s3, 0x7ff
	s_cbranch_scc1 .LBB0_177
	s_load_dwordx4 s[4:7], s[0:1], 0xa8
	v_lshlrev_b32_e32 v1, 4, v1
	v_mov_b32_e32 v51, 0
	v_and_b32_e32 v50, 0xf0, v1
	v_lshrrev_b32_e32 v1, 4, v66
	s_waitcnt lgkmcnt(0)
	v_lshl_add_u64 v[52:53], s[4:5], 0, v[50:51]
	s_bfe_u32 s4, s75, 0x30006
	s_lshl_b32 s5, s4, 15
	s_lshl_b32 s4, s4, 6
	v_lshl_or_b32 v2, v1, 10, s5
	v_lshlrev_b32_e32 v5, 8, v1
	v_or_b32_e32 v6, 4, v1
	v_or_b32_e32 v8, 8, v1
	v_or_b32_e32 v10, 12, v1
	v_or_b32_e32 v12, 16, v1
	v_or_b32_e32 v14, 20, v1
	v_or_b32_e32 v16, 24, v1
	v_or_b32_e32 v1, 28, v1
	s_add_u32 s4, s30, s4
	v_lshl_or_b32 v4, v6, 10, s5
	v_lshlrev_b32_e32 v7, 8, v6
	v_lshl_or_b32 v6, v8, 10, s5
	v_lshlrev_b32_e32 v9, 8, v8
	v_lshl_or_b32 v8, v10, 10, s5
	v_lshlrev_b32_e32 v11, 8, v10
	v_lshl_or_b32 v10, v12, 10, s5
	v_lshlrev_b32_e32 v13, 8, v12
	v_lshl_or_b32 v12, v14, 10, s5
	v_lshlrev_b32_e32 v15, 8, v14
	v_lshl_or_b32 v14, v16, 10, s5
	v_lshlrev_b32_e32 v17, 8, v16
	v_lshl_or_b32 v16, v1, 10, s5
	s_addc_u32 s5, s31, 0
	s_add_u32 s8, s4, 0x4b10000
	v_add_u32_e32 v3, s74, v50
	v_lshlrev_b32_e32 v18, 8, v1
	s_addc_u32 s9, s5, 0
	s_lshl_b32 s4, s2, 6
	s_lshl_b32 s5, s33, 3
	s_add_i32 s10, s4, s5
	s_lshl_b32 s11, s28, 6
	v_lshlrev_b32_e32 v54, 2, v2
	v_mov_b32_e32 v55, v51
	v_add_u32_e32 v1, v3, v5
	v_lshlrev_b32_e32 v56, 2, v4
	v_mov_b32_e32 v57, v51
	v_add_u32_e32 v67, v3, v7
	v_lshlrev_b32_e32 v58, 2, v6
	v_mov_b32_e32 v59, v51
	v_add_u32_e32 v209, v3, v9
	v_lshlrev_b32_e32 v60, 2, v8
	v_mov_b32_e32 v61, v51
	v_add_u32_e32 v211, v3, v11
	v_lshlrev_b32_e32 v62, 2, v10
	v_mov_b32_e32 v63, v51
	v_add_u32_e32 v212, v3, v13
	v_lshlrev_b32_e32 v64, 2, v12
	v_mov_b32_e32 v65, v51
	v_add_u32_e32 v213, v3, v15
	v_lshlrev_b32_e32 v68, 2, v14
	v_mov_b32_e32 v69, v51
	v_add_u32_e32 v214, v3, v17
	v_lshlrev_b32_e32 v70, 2, v16
	v_mov_b32_e32 v71, v51
	v_add_u32_e32 v215, v3, v18
	s_movk_i32 s12, 0x2000
	s_movk_i32 s13, 0x4000
	s_movk_i32 s14, 0x6000
	s_mov_b32 s15, 0x8000
	s_mov_b32 s16, 0xa000
	s_mov_b32 s17, 0xc000
	s_mov_b32 s20, 0xe000
	s_mov_b32 s21, 0x10000
	s_mov_b32 s22, 0x12000
	s_mov_b32 s23, 0x14000
	s_mov_b32 s39, 0x16000
	s_mov_b32 s40, 0x18000
	s_mov_b32 s41, 0x1a000
	s_mov_b32 s42, 0x1c000
	s_mov_b32 s43, 0x1e000
	s_mov_b32 s44, 0x20000
	s_mov_b32 s45, 0x22000
	s_mov_b32 s46, 0x24000
	s_mov_b32 s47, 0x26000
	s_mov_b32 s48, 0x28000
	s_mov_b32 s49, 0x2a000
	s_mov_b32 s50, 0x2c000
	s_mov_b32 s51, 0x2e000
	s_mov_b32 s52, 0x30000
	s_mov_b32 s53, 0x32000
	s_mov_b32 s54, 0x34000
	s_mov_b32 s55, 0x36000
	s_mov_b32 s56, 0x38000
	s_mov_b32 s57, 0x3a000
	s_mov_b32 s58, 0x3c000
	s_mov_b32 s59, 0x3e000
	s_mov_b32 s60, 0x3f000
	s_mov_b32 s61, s3

.LBB0_186:
	s_cmp_eq_u32 s97, 1
	s_cbranch_scc0 .Lp0_bar
	s_mov_b32 s97, 2
	s_branch .Lp0_pre
